# attention tile loop rewritten by hand (depth-3 reg prefetch, K reads upfront, lazy softmax rescale via MFMA C operand, intra-tile QK/softmax/PV interleave) + SSD softplus via compensated hw log
# speedup vs baseline: 1.0079x; 1.0079x over previous
.LBB0_315:
	s_and_saveexec_b64 s[40:41], s[8:9]
	s_cbranch_execz .LBB0_322
	v_lshlrev_b32_e32 v18, 16, v244
	v_add_f32_e32 v18, v242, v18
	s_mov_b32 s33, 0x41a00000
	v_cmp_nlt_f32_e32 vcc, s33, v18
	s_and_saveexec_b64 s[42:43], vcc
	s_cbranch_execz .LBB0_318
	v_mul_f32_e32 v18, 0x3fb8aa3b, v18
	v_exp_f32_e32 v32, v18
	s_nop 0
	v_add_f32_e32 v20, 1.0, v32
	v_log_f32_e32 v21, v20
	v_add_f32_e32 v22, -1.0, v20
	v_rcp_f32_e32 v23, v22
	v_cmp_eq_f32_e32 vcc, 1.0, v20
	v_mul_f32_e32 v21, 0x3f317218, v21
	v_mul_f32_e32 v23, v32, v23
	s_nop 0
	v_mul_f32_e32 v21, v21, v23
	s_nop 0
	v_cndmask_b32_e32 v18, v21, v32, vcc
.LBB0_318:
	s_or_b64 exec, exec, s[42:43]
	v_lshlrev_b32_e32 v19, 16, v245
	v_add_f32_e32 v19, v242, v19
	s_mov_b32 s33, 0x41a00000
	v_cmp_nlt_f32_e32 vcc, s33, v19
	s_and_saveexec_b64 s[42:43], vcc
	s_cbranch_execz .LBB0_320
	v_mul_f32_e32 v19, 0x3fb8aa3b, v19
	v_exp_f32_e32 v19, v19
	s_nop 0
	v_mov_b32_e32 v24, v19
	v_add_f32_e32 v20, 1.0, v24
	v_log_f32_e32 v21, v20
	v_add_f32_e32 v22, -1.0, v20
	v_rcp_f32_e32 v23, v22
	v_cmp_eq_f32_e32 vcc, 1.0, v20
	v_mul_f32_e32 v21, 0x3f317218, v21
	v_mul_f32_e32 v23, v24, v23
	s_nop 0
	v_mul_f32_e32 v21, v21, v23
	s_nop 0
	v_cndmask_b32_e32 v19, v21, v24, vcc

.LBB0_521:
	s_xor_b32 s10, s16, s14
	s_lshl_b32 s8, s10, 8
	s_lshl_b32 s7, s16, 9
	s_and_b32 s11, s8, 0x100
	s_or_b32 s62, s11, s7
	v_lshl_add_u64 v[134:135], v[122:123], 0, s[62:63]
	v_mad_u64_u32 v[2:3], s[8:9], v134, s59, v[124:125]
	v_mov_b32_e32 v0, v3
	v_mad_u64_u32 v[4:5], s[8:9], v135, s59, v[0:1]
	v_mov_b32_e32 v3, v4
	global_load_dwordx4 v[66:69], v[2:3], off
	global_load_dwordx4 v[70:73], v[2:3], off offset:32
	global_load_dwordx4 v[74:77], v[2:3], off offset:64
	global_load_dwordx4 v[78:81], v[2:3], off offset:96
	global_load_dwordx4 v[82:85], v[2:3], off offset:128
	global_load_dwordx4 v[86:89], v[2:3], off offset:160
	s_waitcnt lgkmcnt(0)
	s_barrier
	global_load_dwordx4 v[90:93], v[126:127], off
	global_load_dwordx4 v[94:97], v[126:127], off offset:128
	v_mov_b32_e32 v2, v1
	v_mov_b32_e32 v3, v1
	v_mov_b32_e32 v0, v1
	s_waitcnt vmcnt(16)
	v_mov_b64_e32 v[100:101], v[2:3]
	v_mov_b64_e32 v[98:99], v[0:1]
	global_load_dwordx4 v[98:101], v[128:129], off
	global_load_dwordx4 v[220:223], v[132:133], off
	global_load_dwordx4 v[224:227], v[132:133], off offset:128
	global_load_dwordx4 v[228:231], v[130:131], off
	s_mov_b64 s[24:25], 0x20000
	v_lshl_add_u64 v[136:137], v[132:133], 0, s[24:25]
	v_lshl_add_u64 v[138:139], v[130:131], 0, s[30:31]
	global_load_dwordx4 v[242:245], v[136:137], off
	global_load_dwordx4 v[246:249], v[136:137], off offset:128
	global_load_dwordx4 v[164:167], v[138:139], off
	v_lshl_add_u64 v[136:137], v[136:137], 0, s[24:25]
	v_lshl_add_u64 v[138:139], v[138:139], 0, s[30:31]
	v_add_u32_e32 v0, 0, v112
	s_waitcnt vmcnt(6)
	ds_write_b128 v0, v[90:93]
	v_add_u32_e32 v0, 0, v113
	s_nop 0
	ds_write_b128 v0, v[94:97] offset:13312
	s_and_saveexec_b64 s[8:9], s[0:1]
	v_add_u32_e32 v0, 0, v115
	ds_write_b128 v0, v[98:101] offset:128
	s_or_b64 exec, exec, s[8:9]
	s_add_i32 s8, s15, s11
	s_lshr_b32 s8, s8, 6
	v_mov_b32_e32 v14, v1
	v_mov_b32_e32 v15, v1
	s_waitcnt lgkmcnt(0)
	s_barrier
	s_sub_i32 s18, 0, s8
	s_and_b32 s8, s10, 1
	v_mov_b32_e32 v0, v1
	v_mov_b32_e32 v2, v1
	v_mov_b32_e32 v3, v1
	v_mov_b32_e32 v4, v1
	v_mov_b32_e32 v5, v1
	v_mov_b32_e32 v6, v1
	v_mov_b32_e32 v7, v1
	v_mov_b32_e32 v8, v1
	v_mov_b32_e32 v9, v1
	v_mov_b32_e32 v10, v1
	v_mov_b32_e32 v11, v1
	v_mov_b32_e32 v12, v1
	v_mov_b32_e32 v13, v1
	v_mov_b64_e32 v[32:33], v[14:15]
	s_add_i32 s7, s62, 0x100
	s_lshl_b32 s8, s8, 8
	v_mov_b64_e32 v[30:31], v[12:13]
	v_mov_b64_e32 v[28:29], v[10:11]
	v_mov_b64_e32 v[26:27], v[8:9]
	v_mov_b64_e32 v[24:25], v[6:7]
	v_mov_b64_e32 v[22:23], v[4:5]
	v_mov_b64_e32 v[20:21], v[2:3]
	v_mov_b64_e32 v[18:19], v[0:1]
	v_mov_b64_e32 v[16:17], v[14:15]
	s_lshr_b32 s7, s7, 6
	s_mov_b32 s19, 1
	s_sub_i32 s20, 0, s8
	v_subrev_u32_e32 v121, s11, v114
	v_mov_b32_e32 v144, 0xf149f2ca
	v_mov_b32_e32 v143, 0
	s_nop 0
	s_nop 0
	s_mov_b32 s21, s17
	v_mov_b64_e32 v[14:15], v[12:13]
	v_mov_b64_e32 v[12:13], v[10:11]
	v_mov_b64_e32 v[10:11], v[8:9]
	v_mov_b64_e32 v[8:9], v[6:7]
	v_mov_b64_e32 v[6:7], v[4:5]
	v_mov_b64_e32 v[4:5], v[2:3]
	v_mov_b64_e32 v[2:3], v[0:1]
	v_mov_b32_e32 v146, 0
	v_mov_b32_e32 v147, 0
	v_mov_b32_e32 v148, 0
	v_mov_b32_e32 v149, 0
	v_mov_b32_e32 v150, 0
	v_mov_b32_e32 v151, 0
	v_mov_b32_e32 v152, 0
	v_mov_b32_e32 v153, 0
	v_mov_b32_e32 v154, 0
	v_mov_b32_e32 v155, 0
	v_mov_b32_e32 v156, 0
	v_mov_b32_e32 v157, 0
	v_mov_b32_e32 v158, 0
	v_mov_b32_e32 v159, 0
	v_mov_b32_e32 v160, 0
	v_mov_b32_e32 v161, 0
	s_cmp_lt_u32 s19, s7
	s_cselect_b64 s[8:9], -1, 0
	s_add_i32 s22, s19, -1
	s_add_i32 s12, s22, s18
	s_cmp_gt_i32 s12, -5
	s_cselect_b64 s[10:11], -1, 0
	s_mov_b32 s26, 1
	s_cmp_lt_i32 s12, -4
	s_cbranch_scc1 .Lat_ctl_init
	v_readfirstlane_b32 s13, v109
	s_lshl_b32 s13, s13, 5
	s_add_i32 s12, s20, s21
	s_or_b32 s13, s13, 31
	s_cmp_le_i32 s12, s13
	s_cselect_b32 s26, 1, 0
.Lat_ctl_init:
	s_and_b32 s12, s22, 1
	s_mul_i32 s13, s12, 0x5800
	v_add_u32_e32 v250, s13, v140
	v_add_u32_e32 v251, s13, v141
	s_branch .Lat_head0
.Lat_head0:
	s_andn2_b64 vcc, exec, s[8:9]
	s_cbranch_vccnz .Lat_nostage0
	s_xor_b32 s24, s12, 1
	s_mulk_i32 s24, 0x5800
	s_add_i32 s23, s19, 1
	s_cmp_lt_u32 s23, s7
	s_cbranch_scc1 .Lat_w3_0
	s_waitcnt vmcnt(0)
	s_branch .Lat_wd_0
.Lat_w3_0:
	s_waitcnt vmcnt(3)
.Lat_wd_0:
	v_add_u32_e32 v168, s24, v112
	ds_write_b128 v168, v[220:223]
	v_add_u32_e32 v168, s24, v113
	ds_write_b128 v168, v[224:227] offset:13312
	s_and_saveexec_b64 s[28:29], s[0:1]
	s_cbranch_execz .Lat_wx_0
	v_add_u32_e32 v168, s24, v115
	ds_write_b128 v168, v[228:231] offset:128
.Lat_wx_0:
	s_or_b64 exec, exec, s[28:29]
.Lat_nostage0:
	s_cmp_eq_u32 s26, 0
	s_cbranch_scc1 .Lat_skip0
	ds_read_b128 v[170:173], v250
	ds_read_b128 v[174:177], v250 offset:32
	ds_read_b128 v[178:181], v250 offset:64
	ds_read_b128 v[182:185], v250 offset:96
	ds_read_b128 v[186:189], v250 offset:128
	ds_read_b128 v[190:193], v250 offset:160
	ds_read_b128 v[204:207], v251
	ds_read_b128 v[208:211], v251 offset:32
	s_add_i32 s23, s19, 2
	s_cmp_ge_u32 s23, s7
	s_cbranch_scc1 .Lat_noissue_c0
	global_load_dwordx4 v[90:93], v[136:137], off
	global_load_dwordx4 v[94:97], v[136:137], off offset:128
	global_load_dwordx4 v[98:101], v[138:139], off
.Lat_noissue_c0:
	s_mul_i32 s13, s12, 0x5800
	v_add_u32_e32 v169, s13, v142
	s_waitcnt lgkmcnt(7)
	v_mfma_f32_32x32x16_bf16 v[50:65], v[170:173], v[66:69], v[146:161]
	ds_read_b128 v[170:173], v251 offset:64
	s_waitcnt lgkmcnt(7)
	v_mfma_f32_32x32x16_bf16 v[50:65], v[174:177], v[70:73], v[50:65]
	ds_read_b128 v[174:177], v251 offset:96
	s_waitcnt lgkmcnt(7)
	v_mfma_f32_32x32x16_bf16 v[50:65], v[178:181], v[74:77], v[50:65]
	ds_read_b128 v[178:181], v251 offset:128
	s_waitcnt lgkmcnt(7)
	v_mfma_f32_32x32x16_bf16 v[50:65], v[182:185], v[78:81], v[50:65]
	ds_read_b128 v[182:185], v251 offset:160
	s_waitcnt lgkmcnt(7)
	v_mfma_f32_32x32x16_bf16 v[50:65], v[186:189], v[82:85], v[50:65]
	s_waitcnt lgkmcnt(6)
	v_mfma_f32_32x32x16_bf16 v[50:65], v[190:193], v[86:89], v[50:65]
	ds_read_b64_tr_b16 v[186:187], v169 offset:13312
	ds_read_b64_tr_b16 v[188:189], v169 offset:14464
	ds_read_b64_tr_b16 v[190:191], v169 offset:13376
	ds_read_b64_tr_b16 v[192:193], v169 offset:14528
	s_nop 7
	s_andn2_b64 vcc, exec, s[10:11]
	s_cbranch_vccnz .Lat_nomaskA0
	v_add_u32_e32 v0, s21, v121
	v_mov_b32_e32 v145, v0
	v_add_u32_e32 v168, 1, v0
	v_cmp_le_i32_e64 vcc, v145, v102
	v_add_u32_e32 v252, 2, v0
	v_cmp_le_i32_e64 s[28:29], v168, v102
	v_cndmask_b32_e64 v50, v203, v50, vcc
	v_add_u32_e32 v145, 3, v0
	v_cmp_le_i32_e64 vcc, v252, v102
	v_cndmask_b32_e64 v51, v203, v51, s[28:29]
	v_add_u32_e32 v168, 8, v0
	v_cmp_le_i32_e64 s[28:29], v145, v102
	v_cndmask_b32_e64 v52, v203, v52, vcc
	v_add_u32_e32 v252, 9, v0
	v_cmp_le_i32_e64 vcc, v168, v102
	v_cndmask_b32_e64 v53, v203, v53, s[28:29]
	v_add_u32_e32 v145, 10, v0
	v_cmp_le_i32_e64 s[28:29], v252, v102
	v_cndmask_b32_e64 v54, v203, v54, vcc
	v_add_u32_e32 v168, 11, v0
	v_cmp_le_i32_e64 vcc, v145, v102
	v_cndmask_b32_e64 v55, v203, v55, s[28:29]
	v_add_u32_e32 v252, 16, v0
	v_cmp_le_i32_e64 s[28:29], v168, v102
	v_cndmask_b32_e64 v56, v203, v56, vcc
	v_add_u32_e32 v145, 17, v0
	v_cmp_le_i32_e64 vcc, v252, v102
	v_cndmask_b32_e64 v57, v203, v57, s[28:29]
	v_add_u32_e32 v168, 18, v0
	v_cmp_le_i32_e64 s[28:29], v145, v102
	v_cndmask_b32_e64 v58, v203, v58, vcc
	v_add_u32_e32 v252, 19, v0
	v_cmp_le_i32_e64 vcc, v168, v102
	v_cndmask_b32_e64 v59, v203, v59, s[28:29]
	v_add_u32_e32 v145, 24, v0
	v_cmp_le_i32_e64 s[28:29], v252, v102
	v_cndmask_b32_e64 v60, v203, v60, vcc
	v_add_u32_e32 v168, 25, v0
	v_cmp_le_i32_e64 vcc, v145, v102
	v_cndmask_b32_e64 v61, v203, v61, s[28:29]
	v_add_u32_e32 v252, 26, v0
	v_cmp_le_i32_e64 s[28:29], v168, v102
	v_cndmask_b32_e64 v62, v203, v62, vcc
	v_add_u32_e32 v145, 27, v0
	v_cmp_le_i32_e64 vcc, v252, v102
	v_cndmask_b32_e64 v63, v203, v63, s[28:29]
	v_cmp_le_i32_e64 s[28:29], v145, v102
	v_cndmask_b32_e64 v64, v203, v64, vcc
	s_nop 1
	v_cndmask_b32_e64 v65, v203, v65, s[28:29]
.Lat_nomaskA0:
	v_max3_f32 v232, v50, v51, v52
	v_max3_f32 v233, v53, v54, v55
	v_max3_f32 v232, v232, v56, v57
	v_max3_f32 v233, v233, v58, v59
	v_max3_f32 v232, v232, v60, v61
	v_max3_f32 v233, v233, v62, v63
	v_max3_f32 v232, v232, v64, v65
	v_max_f32_e32 v232, v232, v233
	v_mov_b32_e32 v233, v232
	s_nop 1
	v_permlane32_swap_b32_e32 v232, v233
	v_max_f32_e32 v232, v232, v233
	v_cmp_lt_f32_e32 vcc, 0x41000000, v232
	s_cmp_eq_u32 s22, 0
	s_cbranch_scc1 .Lat_firstA0
	s_cbranch_vccnz .Lat_rareA0
.Lat_commonA0:
	s_waitcnt lgkmcnt(9)
	v_mfma_f32_32x32x16_bf16 v[34:49], v[204:207], v[66:69], v[146:161]
	ds_read_b64_tr_b16 v[204:205], v169 offset:15616
	ds_read_b64_tr_b16 v[206:207], v169 offset:16768
	v_exp_f32_e32 v50, v50
	v_exp_f32_e32 v51, v51
	v_exp_f32_e32 v52, v52
	v_exp_f32_e32 v53, v53
	s_waitcnt lgkmcnt(10)
	v_mfma_f32_32x32x16_bf16 v[34:49], v[208:211], v[70:73], v[34:49]
	ds_read_b64_tr_b16 v[208:209], v169 offset:15680
	ds_read_b64_tr_b16 v[210:211], v169 offset:16832
	v_exp_f32_e32 v54, v54
	v_exp_f32_e32 v55, v55
	v_exp_f32_e32 v56, v56
	v_exp_f32_e32 v57, v57
	v_cvt_pk_bf16_f32 v212, v50, v51
	v_cvt_pk_bf16_f32 v213, v52, v53
	v_cvt_pk_bf16_f32 v214, v54, v55
	v_cvt_pk_bf16_f32 v215, v56, v57
	s_waitcnt lgkmcnt(11)
	v_mfma_f32_32x32x16_bf16 v[34:49], v[170:173], v[74:77], v[34:49]
	v_add_f32_e32 v143, v143, v50
	v_add_f32_e32 v143, v143, v52
	v_add_f32_e32 v237, v51, v53
	s_waitcnt lgkmcnt(6)
	v_mfma_f32_32x32x16_bf16 v[18:33], v[186:189], v[212:215], v[18:33]
	v_exp_f32_e32 v58, v58
	v_exp_f32_e32 v59, v59
	v_exp_f32_e32 v60, v60
	s_waitcnt lgkmcnt(4)
	v_mfma_f32_32x32x16_bf16 v[2:17], v[190:193], v[212:215], v[2:17]
	v_exp_f32_e32 v61, v61
	v_exp_f32_e32 v62, v62
	v_exp_f32_e32 v63, v63
	v_mfma_f32_32x32x16_bf16 v[34:49], v[174:177], v[78:81], v[34:49]
	v_exp_f32_e32 v64, v64
	v_exp_f32_e32 v65, v65
	v_add_f32_e32 v143, v143, v54
	v_add_f32_e32 v237, v237, v55
	v_mfma_f32_32x32x16_bf16 v[34:49], v[178:181], v[82:85], v[34:49]
	v_cvt_pk_bf16_f32 v216, v58, v59
	v_cvt_pk_bf16_f32 v217, v60, v61
	v_cvt_pk_bf16_f32 v218, v62, v63
	v_cvt_pk_bf16_f32 v219, v64, v65
	v_mfma_f32_32x32x16_bf16 v[34:49], v[182:185], v[86:89], v[34:49]
	v_add_f32_e32 v143, v143, v56
	v_add_f32_e32 v237, v237, v57
	v_add_f32_e32 v143, v143, v58
	v_add_f32_e32 v237, v237, v59
	s_waitcnt lgkmcnt(2)
	v_mfma_f32_32x32x16_bf16 v[18:33], v[204:207], v[216:219], v[18:33]
	v_add_f32_e32 v143, v143, v60
	v_add_f32_e32 v237, v237, v61
	v_add_f32_e32 v143, v143, v62
	s_waitcnt lgkmcnt(0)
	v_mfma_f32_32x32x16_bf16 v[2:17], v[208:211], v[216:219], v[2:17]
	v_add_f32_e32 v237, v237, v63
	v_add_f32_e32 v143, v143, v64
	v_add_f32_e32 v237, v237, v65
	ds_read_b64_tr_b16 v[170:171], v169 offset:17920
	ds_read_b64_tr_b16 v[172:173], v169 offset:19072
	ds_read_b64_tr_b16 v[174:175], v169 offset:17984
	ds_read_b64_tr_b16 v[176:177], v169 offset:19136
	ds_read_b64_tr_b16 v[178:179], v169 offset:20224
	ds_read_b64_tr_b16 v[180:181], v169 offset:21376
	ds_read_b64_tr_b16 v[182:183], v169 offset:20288
	ds_read_b64_tr_b16 v[184:185], v169 offset:21440
	s_nop 1
	s_andn2_b64 vcc, exec, s[10:11]
	s_cbranch_vccnz .Lat_nomaskB0
	v_add_u32_e32 v0, s21, v121
	v_add_u32_e32 v145, 32, v0
	v_add_u32_e32 v168, 33, v0
	v_cmp_le_i32_e64 vcc, v145, v102
	v_add_u32_e32 v252, 34, v0
	v_cmp_le_i32_e64 s[28:29], v168, v102
	v_cndmask_b32_e64 v34, v203, v34, vcc
	v_add_u32_e32 v145, 35, v0
	v_cmp_le_i32_e64 vcc, v252, v102
	v_cndmask_b32_e64 v35, v203, v35, s[28:29]
	v_add_u32_e32 v168, 40, v0
	v_cmp_le_i32_e64 s[28:29], v145, v102
	v_cndmask_b32_e64 v36, v203, v36, vcc
	v_add_u32_e32 v252, 41, v0
	v_cmp_le_i32_e64 vcc, v168, v102
	v_cndmask_b32_e64 v37, v203, v37, s[28:29]
	v_add_u32_e32 v145, 42, v0
	v_cmp_le_i32_e64 s[28:29], v252, v102
	v_cndmask_b32_e64 v38, v203, v38, vcc
	v_add_u32_e32 v168, 43, v0
	v_cmp_le_i32_e64 vcc, v145, v102
	v_cndmask_b32_e64 v39, v203, v39, s[28:29]
	v_add_u32_e32 v252, 48, v0
	v_cmp_le_i32_e64 s[28:29], v168, v102
	v_cndmask_b32_e64 v40, v203, v40, vcc
	v_add_u32_e32 v145, 49, v0
	v_cmp_le_i32_e64 vcc, v252, v102
	v_cndmask_b32_e64 v41, v203, v41, s[28:29]
	v_add_u32_e32 v168, 50, v0
	v_cmp_le_i32_e64 s[28:29], v145, v102
	v_cndmask_b32_e64 v42, v203, v42, vcc
	v_add_u32_e32 v252, 51, v0
	v_cmp_le_i32_e64 vcc, v168, v102
	v_cndmask_b32_e64 v43, v203, v43, s[28:29]
	v_add_u32_e32 v145, 56, v0
	v_cmp_le_i32_e64 s[28:29], v252, v102
	v_cndmask_b32_e64 v44, v203, v44, vcc
	v_add_u32_e32 v168, 57, v0
	v_cmp_le_i32_e64 vcc, v145, v102
	v_cndmask_b32_e64 v45, v203, v45, s[28:29]
	v_add_u32_e32 v252, 58, v0
	v_cmp_le_i32_e64 s[28:29], v168, v102
	v_cndmask_b32_e64 v46, v203, v46, vcc
	v_add_u32_e32 v145, 59, v0
	v_cmp_le_i32_e64 vcc, v252, v102
	v_cndmask_b32_e64 v47, v203, v47, s[28:29]
	v_cmp_le_i32_e64 s[28:29], v145, v102
	v_cndmask_b32_e64 v48, v203, v48, vcc
	s_nop 1
	v_cndmask_b32_e64 v49, v203, v49, s[28:29]
.Lat_nomaskB0:
	v_max3_f32 v232, v34, v35, v36
	v_max3_f32 v233, v37, v38, v39
	v_max3_f32 v232, v232, v40, v41
	v_max3_f32 v233, v233, v42, v43
	v_max3_f32 v232, v232, v44, v45
	v_max3_f32 v233, v233, v46, v47
	v_max3_f32 v232, v232, v48, v49
	v_max_f32_e32 v232, v232, v233
	v_mov_b32_e32 v233, v232
	s_nop 1
	v_permlane32_swap_b32_e32 v232, v233
	v_max_f32_e32 v232, v232, v233
	v_cmp_lt_f32_e32 vcc, 0x41000000, v232
	s_cbranch_vccnz .Lat_rareB0
.Lat_commonB0:
	v_exp_f32_e32 v34, v34
	v_exp_f32_e32 v35, v35
	v_exp_f32_e32 v36, v36
	v_exp_f32_e32 v37, v37
	v_exp_f32_e32 v38, v38
	v_exp_f32_e32 v39, v39
	v_exp_f32_e32 v40, v40
	v_exp_f32_e32 v41, v41
	v_cvt_pk_bf16_f32 v212, v34, v35
	v_cvt_pk_bf16_f32 v213, v36, v37
	v_cvt_pk_bf16_f32 v214, v38, v39
	v_cvt_pk_bf16_f32 v215, v40, v41
	v_exp_f32_e32 v42, v42
	v_exp_f32_e32 v43, v43
	s_waitcnt lgkmcnt(6)
	v_mfma_f32_32x32x16_bf16 v[18:33], v[170:173], v[212:215], v[18:33]
	s_waitcnt lgkmcnt(4)
	v_mfma_f32_32x32x16_bf16 v[2:17], v[174:177], v[212:215], v[2:17]
	v_exp_f32_e32 v44, v44
	v_add_f32_e32 v143, v143, v34
	v_exp_f32_e32 v45, v45
	v_add_f32_e32 v237, v237, v35
	v_exp_f32_e32 v46, v46
	v_add_f32_e32 v143, v143, v36
	v_exp_f32_e32 v47, v47
	v_add_f32_e32 v237, v237, v37
	v_exp_f32_e32 v48, v48
	v_add_f32_e32 v143, v143, v38
	v_exp_f32_e32 v49, v49
	v_add_f32_e32 v237, v237, v39
	v_add_f32_e32 v143, v143, v40
	v_add_f32_e32 v237, v237, v41
	v_cvt_pk_bf16_f32 v216, v42, v43
	v_cvt_pk_bf16_f32 v217, v44, v45
	v_cvt_pk_bf16_f32 v218, v46, v47
	v_cvt_pk_bf16_f32 v219, v48, v49
	v_add_f32_e32 v143, v143, v42
	v_add_f32_e32 v237, v237, v43
	s_waitcnt lgkmcnt(2)
	v_mfma_f32_32x32x16_bf16 v[18:33], v[178:181], v[216:219], v[18:33]
	s_waitcnt lgkmcnt(0)
	v_mfma_f32_32x32x16_bf16 v[2:17], v[182:185], v[216:219], v[2:17]
	v_add_f32_e32 v143, v143, v44
	v_add_f32_e32 v237, v237, v45
	v_add_f32_e32 v143, v143, v46
	v_add_f32_e32 v237, v237, v47
	v_add_f32_e32 v143, v143, v48
	v_add_f32_e32 v237, v237, v49
	v_add_f32_e32 v143, v143, v237
	s_branch .Lat_tail0
.Lat_skip0:
	s_add_i32 s23, s19, 2
	s_cmp_ge_u32 s23, s7
	s_cbranch_scc1 .Lat_noissue_s0
	global_load_dwordx4 v[90:93], v[136:137], off
	global_load_dwordx4 v[94:97], v[136:137], off offset:128
	global_load_dwordx4 v[98:101], v[138:139], off
.Lat_noissue_s0:
.Lat_tail0:
	s_add_i32 s19, s19, 1
	s_add_i32 s21, s21, 64
	s_mov_b64 s[28:29], 0x20000
	v_lshl_add_u64 v[138:139], v[138:139], 0, s[30:31]
	v_lshl_add_u64 v[136:137], v[136:137], 0, s[28:29]
	s_add_i32 s8, s18, s19
	s_cmp_lg_u32 s8, 1
	s_cselect_b32 s25, 0, 1
	s_cmp_lt_u32 s19, s7
	s_cselect_b64 s[8:9], -1, 0
	s_add_i32 s22, s19, -1
	s_add_i32 s12, s22, s18
	s_cmp_gt_i32 s12, -5
	s_cselect_b64 s[10:11], -1, 0
	s_mov_b32 s26, 1
	s_cmp_lt_i32 s12, -4
	s_cbranch_scc1 .Lat_ctl_t0
	v_readfirstlane_b32 s13, v109
	s_lshl_b32 s13, s13, 5
	s_add_i32 s12, s20, s21
	s_or_b32 s13, s13, 31
	s_cmp_le_i32 s12, s13
	s_cselect_b32 s26, 1, 0
.Lat_ctl_t0:
	s_and_b32 s12, s22, 1
	s_mul_i32 s13, s12, 0x5800
	v_add_u32_e32 v250, s13, v140
	v_add_u32_e32 v251, s13, v141
	s_waitcnt lgkmcnt(0)
	s_barrier
	s_cmp_eq_u32 s25, 1
	s_cbranch_scc1 .LBB0_520

.Lat_wd_1:
	v_add_u32_e32 v168, s24, v112
	ds_write_b128 v168, v[242:245]
	v_add_u32_e32 v168, s24, v113
	ds_write_b128 v168, v[246:249] offset:13312
	s_and_saveexec_b64 s[28:29], s[0:1]
	s_cbranch_execz .Lat_wx_1
	v_add_u32_e32 v168, s24, v115
	ds_write_b128 v168, v[164:167] offset:128

.Lat_nostage1:
	s_cmp_eq_u32 s26, 0
	s_cbranch_scc1 .Lat_skip1
	ds_read_b128 v[170:173], v250
	ds_read_b128 v[174:177], v250 offset:32
	ds_read_b128 v[178:181], v250 offset:64
	ds_read_b128 v[182:185], v250 offset:96
	ds_read_b128 v[186:189], v250 offset:128
	ds_read_b128 v[190:193], v250 offset:160
	ds_read_b128 v[204:207], v251
	ds_read_b128 v[208:211], v251 offset:32
	s_add_i32 s23, s19, 2
	s_cmp_ge_u32 s23, s7
	s_cbranch_scc1 .Lat_noissue_c1
	global_load_dwordx4 v[220:223], v[136:137], off
	global_load_dwordx4 v[224:227], v[136:137], off offset:128
	global_load_dwordx4 v[228:231], v[138:139], off

.Lat_skip1:
	s_add_i32 s23, s19, 2
	s_cmp_ge_u32 s23, s7
	s_cbranch_scc1 .Lat_noissue_s1
	global_load_dwordx4 v[220:223], v[136:137], off
	global_load_dwordx4 v[224:227], v[136:137], off offset:128
	global_load_dwordx4 v[228:231], v[138:139], off

.Lat_wd_2:
	v_add_u32_e32 v168, s24, v112
	ds_write_b128 v168, v[90:93]
	v_add_u32_e32 v168, s24, v113
	ds_write_b128 v168, v[94:97] offset:13312
	s_and_saveexec_b64 s[28:29], s[0:1]
	s_cbranch_execz .Lat_wx_2
	v_add_u32_e32 v168, s24, v115
	ds_write_b128 v168, v[98:101] offset:128

.Lat_nostage2:
	s_cmp_eq_u32 s26, 0
	s_cbranch_scc1 .Lat_skip2
	ds_read_b128 v[170:173], v250
	ds_read_b128 v[174:177], v250 offset:32
	ds_read_b128 v[178:181], v250 offset:64
	ds_read_b128 v[182:185], v250 offset:96
	ds_read_b128 v[186:189], v250 offset:128
	ds_read_b128 v[190:193], v250 offset:160
	ds_read_b128 v[204:207], v251
	ds_read_b128 v[208:211], v251 offset:32
	s_add_i32 s23, s19, 2
	s_cmp_ge_u32 s23, s7
	s_cbranch_scc1 .Lat_noissue_c2
	global_load_dwordx4 v[242:245], v[136:137], off
	global_load_dwordx4 v[246:249], v[136:137], off offset:128
	global_load_dwordx4 v[164:167], v[138:139], off

.Lat_skip2:
	s_add_i32 s23, s19, 2
	s_cmp_ge_u32 s23, s7
	s_cbranch_scc1 .Lat_noissue_s2
	global_load_dwordx4 v[242:245], v[136:137], off
	global_load_dwordx4 v[246:249], v[136:137], off offset:128
	global_load_dwordx4 v[164:167], v[138:139], off

.Lat_ctl_t2:
	s_and_b32 s12, s22, 1
	s_mul_i32 s13, s12, 0x5800
	v_add_u32_e32 v250, s13, v140
	v_add_u32_e32 v251, s13, v141
	s_waitcnt lgkmcnt(0)
	s_barrier
	s_cmp_eq_u32 s25, 1
	s_cbranch_scc1 .LBB0_520
	s_branch .Lat_head0
.Lat_rareA0:
	v_max_f32_e32 v232, 0, v232
	v_exp_f32_e64 v233, -v232
	v_sub_f32_e32 v50, v50, v232
	v_sub_f32_e32 v51, v51, v232
	v_sub_f32_e32 v52, v52, v232
	v_sub_f32_e32 v53, v53, v232
	v_sub_f32_e32 v54, v54, v232
	v_sub_f32_e32 v55, v55, v232
	v_sub_f32_e32 v56, v56, v232
	v_sub_f32_e32 v57, v57, v232
	v_sub_f32_e32 v58, v58, v232
	v_sub_f32_e32 v59, v59, v232
	v_sub_f32_e32 v60, v60, v232
	v_sub_f32_e32 v61, v61, v232
	v_sub_f32_e32 v62, v62, v232
	v_sub_f32_e32 v63, v63, v232
	v_sub_f32_e32 v64, v64, v232
	v_sub_f32_e32 v65, v65, v232
	v_sub_f32_e32 v146, v146, v232
	v_mul_f32_e32 v18, v18, v233
	v_mul_f32_e32 v19, v19, v233
	v_mul_f32_e32 v20, v20, v233
	v_mul_f32_e32 v21, v21, v233
	v_mul_f32_e32 v22, v22, v233
	v_mul_f32_e32 v23, v23, v233
	v_mul_f32_e32 v24, v24, v233
	v_mul_f32_e32 v25, v25, v233
	v_mul_f32_e32 v26, v26, v233
	v_mul_f32_e32 v27, v27, v233
	v_mul_f32_e32 v28, v28, v233
	v_mul_f32_e32 v29, v29, v233
	v_mul_f32_e32 v30, v30, v233
	v_mul_f32_e32 v31, v31, v233
	v_mul_f32_e32 v32, v32, v233
	v_mul_f32_e32 v33, v33, v233
	v_mul_f32_e32 v2, v2, v233
	v_mul_f32_e32 v3, v3, v233
	v_mul_f32_e32 v4, v4, v233
	v_mul_f32_e32 v5, v5, v233
	v_mul_f32_e32 v6, v6, v233
	v_mul_f32_e32 v7, v7, v233
	v_mul_f32_e32 v8, v8, v233
	v_mul_f32_e32 v9, v9, v233
	v_mul_f32_e32 v10, v10, v233
	v_mul_f32_e32 v11, v11, v233
	v_mul_f32_e32 v12, v12, v233
	v_mul_f32_e32 v13, v13, v233
	v_mul_f32_e32 v14, v14, v233
	v_mul_f32_e32 v15, v15, v233
	v_mul_f32_e32 v16, v16, v233
	v_mul_f32_e32 v17, v17, v233
	v_mul_f32_e32 v143, v143, v233
	v_mov_b32_e32 v147, v146
	v_mov_b32_e32 v148, v146
	v_mov_b32_e32 v149, v146
	v_mov_b32_e32 v150, v146
	v_mov_b32_e32 v151, v146
	v_mov_b32_e32 v152, v146
	v_mov_b32_e32 v153, v146
	v_mov_b32_e32 v154, v146
	v_mov_b32_e32 v155, v146
	v_mov_b32_e32 v156, v146
	v_mov_b32_e32 v157, v146
	v_mov_b32_e32 v158, v146
	v_mov_b32_e32 v159, v146
	v_mov_b32_e32 v160, v146
	v_mov_b32_e32 v161, v146
	s_nop 1
	s_branch .Lat_commonA0
.Lat_firstA0:
	v_sub_f32_e32 v50, v50, v232
	v_sub_f32_e32 v51, v51, v232
	v_sub_f32_e32 v52, v52, v232
	v_sub_f32_e32 v53, v53, v232
	v_sub_f32_e32 v54, v54, v232
	v_sub_f32_e32 v55, v55, v232
	v_sub_f32_e32 v56, v56, v232
	v_sub_f32_e32 v57, v57, v232
	v_sub_f32_e32 v58, v58, v232
	v_sub_f32_e32 v59, v59, v232
	v_sub_f32_e32 v60, v60, v232
	v_sub_f32_e32 v61, v61, v232
	v_sub_f32_e32 v62, v62, v232
	v_sub_f32_e32 v63, v63, v232
	v_sub_f32_e32 v64, v64, v232
	v_sub_f32_e32 v65, v65, v232
	v_sub_f32_e32 v146, v146, v232
	s_nop 0
	v_mov_b32_e32 v147, v146
	v_mov_b32_e32 v148, v146
	v_mov_b32_e32 v149, v146
	v_mov_b32_e32 v150, v146
	v_mov_b32_e32 v151, v146
	v_mov_b32_e32 v152, v146
	v_mov_b32_e32 v153, v146
	v_mov_b32_e32 v154, v146
	v_mov_b32_e32 v155, v146
	v_mov_b32_e32 v156, v146
	v_mov_b32_e32 v157, v146
	v_mov_b32_e32 v158, v146
	v_mov_b32_e32 v159, v146
	v_mov_b32_e32 v160, v146
	v_mov_b32_e32 v161, v146
	s_nop 1
	s_branch .Lat_commonA0
.Lat_rareB0:
	v_max_f32_e32 v232, 0, v232
	v_exp_f32_e64 v233, -v232
	v_sub_f32_e32 v34, v34, v232
	v_sub_f32_e32 v35, v35, v232
	v_sub_f32_e32 v36, v36, v232
	v_sub_f32_e32 v37, v37, v232
	v_sub_f32_e32 v38, v38, v232
	v_sub_f32_e32 v39, v39, v232
	v_sub_f32_e32 v40, v40, v232
	v_sub_f32_e32 v41, v41, v232
	v_sub_f32_e32 v42, v42, v232
	v_sub_f32_e32 v43, v43, v232
	v_sub_f32_e32 v44, v44, v232
	v_sub_f32_e32 v45, v45, v232
	v_sub_f32_e32 v46, v46, v232
	v_sub_f32_e32 v47, v47, v232
	v_sub_f32_e32 v48, v48, v232
	v_sub_f32_e32 v49, v49, v232
	v_sub_f32_e32 v146, v146, v232
	v_mul_f32_e32 v143, v143, v233
	v_mul_f32_e32 v237, v237, v233
	v_mov_b32_e32 v147, v146
	v_mov_b32_e32 v148, v146
	v_mov_b32_e32 v149, v146
	v_mov_b32_e32 v150, v146
	v_mov_b32_e32 v151, v146
	v_mov_b32_e32 v152, v146
	v_mov_b32_e32 v153, v146
	v_mov_b32_e32 v154, v146
	v_mov_b32_e32 v155, v146
	v_mov_b32_e32 v156, v146
	v_mov_b32_e32 v157, v146
	v_mov_b32_e32 v158, v146
	v_mov_b32_e32 v159, v146
	v_mov_b32_e32 v160, v146
	v_mov_b32_e32 v161, v146
	v_mul_f32_e32 v18, v18, v233
	v_mul_f32_e32 v19, v19, v233
	v_mul_f32_e32 v20, v20, v233
	v_mul_f32_e32 v21, v21, v233
	v_mul_f32_e32 v22, v22, v233
	v_mul_f32_e32 v23, v23, v233
	v_mul_f32_e32 v24, v24, v233
	v_mul_f32_e32 v25, v25, v233
	v_mul_f32_e32 v26, v26, v233
	v_mul_f32_e32 v27, v27, v233
	v_mul_f32_e32 v28, v28, v233
	v_mul_f32_e32 v29, v29, v233
	v_mul_f32_e32 v30, v30, v233
	v_mul_f32_e32 v31, v31, v233
	v_mul_f32_e32 v32, v32, v233
	v_mul_f32_e32 v33, v33, v233
	v_mul_f32_e32 v2, v2, v233
	v_mul_f32_e32 v3, v3, v233
	v_mul_f32_e32 v4, v4, v233
	v_mul_f32_e32 v5, v5, v233
	v_mul_f32_e32 v6, v6, v233
	v_mul_f32_e32 v7, v7, v233
	v_mul_f32_e32 v8, v8, v233
	v_mul_f32_e32 v9, v9, v233
	v_mul_f32_e32 v10, v10, v233
	v_mul_f32_e32 v11, v11, v233
	v_mul_f32_e32 v12, v12, v233
	v_mul_f32_e32 v13, v13, v233
	v_mul_f32_e32 v14, v14, v233
	v_mul_f32_e32 v15, v15, v233
	v_mul_f32_e32 v16, v16, v233
	v_mul_f32_e32 v17, v17, v233
	s_nop 1
	s_branch .Lat_commonB0
